# scan y flush address = per-lane part + scalar chunk offset (3 VALU instead of 13 per chunk), on top of the batched y reduce-scatter
# baseline (speedup 1.0000x reference)
; __device__ __forceinline__ void rwkv_scan_unit(const Params& p, int unit, char* smem) {
;     ...
;             const int u = tid >> 4, r = tid & 15;
;             Yb[((size_t)b * TT + step_tok(ci * SCH + u, d)) * 1024 + r] = f2bf(*((const float*)(smem + YOFF + (ci & 1) * 1024) + u * 16 + r));
.LBB0_380:
	global_load_dword v39, v[152:153], off
	v_add_u32_e32 v87, 16, v87
	v_add_u32_e32 v85, 16, v85
	v_add_u32_e32 v83, 16, v83
	v_add_u32_e32 v88, -16, v88
	v_add_u32_e32 v86, -16, v86
	v_add_u32_e32 v84, -16, v84
	v_add_u32_e32 v142, s55, v87
	v_cmp_lt_i32_e32 vcc, s2, v142
	s_nop 1
	v_cndmask_b32_e32 v143, v196, v197, vcc
	v_add_u32_e32 v143, v143, v88
	v_cndmask_b32_e64 v142, v143, v142, s[44:45]
	v_ashrrev_i32_e32 v143, 31, v142
	v_lshl_add_u64 v[142:143], v[142:143], 0, s[88:89]
	v_lshlrev_b64 v[142:143], 9, v[142:143]
	v_lshl_add_u64 v[140:141], v[152:153], 0, v[142:143]
	global_load_dwordx4 v[140:143], v[140:141], off
	v_add_u32_e32 v146, s55, v85
	v_cmp_lt_i32_e32 vcc, s2, v146
	s_nop 1
	v_cndmask_b32_e32 v147, v196, v197, vcc
	v_add_u32_e32 v147, v147, v86
	v_cndmask_b32_e64 v146, v147, v146, s[44:45]
	v_ashrrev_i32_e32 v147, 31, v146
	v_lshl_add_u64 v[146:147], v[146:147], 0, s[88:89]
	v_lshlrev_b64 v[146:147], 9, v[146:147]
	v_lshl_add_u64 v[144:145], v[154:155], 0, v[146:147]
	global_load_dwordx4 v[144:147], v[144:145], off
	v_add_u32_e32 v150, s55, v83
	v_cmp_lt_i32_e32 vcc, s2, v150
	s_nop 1
	v_cndmask_b32_e32 v151, v196, v197, vcc
	v_add_u32_e32 v151, v151, v84
	v_cndmask_b32_e64 v150, v151, v150, s[44:45]
	v_ashrrev_i32_e32 v151, 31, v150
	v_lshl_add_u64 v[150:151], v[150:151], 0, s[88:89]
	v_lshlrev_b64 v[150:151], 9, v[150:151]
	v_lshl_add_u64 v[148:149], v[156:157], 0, v[150:151]
	global_load_dwordx4 v[148:151], v[148:149], off
	global_load_dword v39, v[152:153], off
	v_add_u32_e32 v87, 16, v87
	v_add_u32_e32 v85, 16, v85
	v_add_u32_e32 v83, 16, v83
	v_add_u32_e32 v88, -16, v88
	v_add_u32_e32 v86, -16, v86
	v_add_u32_e32 v84, -16, v84
	v_add_u32_e32 v126, s55, v87
	v_cmp_lt_i32_e32 vcc, s2, v126
	s_nop 1
	v_cndmask_b32_e32 v127, v196, v197, vcc
	v_add_u32_e32 v127, v127, v88
	v_cndmask_b32_e64 v126, v127, v126, s[44:45]
	v_ashrrev_i32_e32 v127, 31, v126
	v_lshl_add_u64 v[126:127], v[126:127], 0, s[88:89]
	v_lshlrev_b64 v[126:127], 9, v[126:127]
	v_lshl_add_u64 v[124:125], v[152:153], 0, v[126:127]
	global_load_dwordx4 v[124:127], v[124:125], off
	v_add_u32_e32 v130, s55, v85
	v_cmp_lt_i32_e32 vcc, s2, v130
	s_nop 1
	v_cndmask_b32_e32 v131, v196, v197, vcc
	v_add_u32_e32 v131, v131, v86
	v_cndmask_b32_e64 v130, v131, v130, s[44:45]
	v_ashrrev_i32_e32 v131, 31, v130
	v_lshl_add_u64 v[130:131], v[130:131], 0, s[88:89]
	v_lshlrev_b64 v[130:131], 9, v[130:131]
	v_lshl_add_u64 v[128:129], v[154:155], 0, v[130:131]
	global_load_dwordx4 v[128:131], v[128:129], off
	v_add_u32_e32 v134, s55, v83
	v_cmp_lt_i32_e32 vcc, s2, v134
	s_nop 1
	v_cndmask_b32_e32 v135, v196, v197, vcc
	v_add_u32_e32 v135, v135, v84
	v_cndmask_b32_e64 v134, v135, v134, s[44:45]
	v_ashrrev_i32_e32 v135, 31, v134
	v_lshl_add_u64 v[134:135], v[134:135], 0, s[88:89]
	v_lshlrev_b64 v[134:135], 9, v[134:135]
	v_lshl_add_u64 v[132:133], v[156:157], 0, v[134:135]
	global_load_dwordx4 v[132:135], v[132:133], off
	global_load_dword v39, v[152:153], off
	v_add_u32_e32 v87, 16, v87
	v_add_u32_e32 v85, 16, v85
	v_add_u32_e32 v83, 16, v83
	v_add_u32_e32 v88, -16, v88
	v_add_u32_e32 v86, -16, v86
	v_add_u32_e32 v84, -16, v84
	v_add_u32_e32 v230, s55, v88
	v_cndmask_b32_e64 v230, v230, v87, s[44:45]
	v_ashrrev_i32_e32 v231, 31, v230
	v_lshl_add_u64 v[230:231], v[230:231], 0, s[88:89]
	v_lshlrev_b64 v[230:231], 9, v[230:231]
	v_lshl_add_u64 v[224:225], v[152:153], 0, v[230:231]
	v_add_u32_e32 v230, s55, v86
	v_cndmask_b32_e64 v230, v230, v85, s[44:45]
	v_ashrrev_i32_e32 v231, 31, v230
	v_lshl_add_u64 v[230:231], v[230:231], 0, s[88:89]
	v_lshlrev_b64 v[230:231], 9, v[230:231]
	v_lshl_add_u64 v[226:227], v[154:155], 0, v[230:231]
	v_add_u32_e32 v230, s55, v84
	v_cndmask_b32_e64 v230, v230, v83, s[44:45]
	v_ashrrev_i32_e32 v231, 31, v230
	v_lshl_add_u64 v[230:231], v[230:231], 0, s[88:89]
	v_lshlrev_b64 v[230:231], 9, v[230:231]
	v_lshl_add_u64 v[228:229], v[156:157], 0, v[230:231]
	v_lshlrev_b32_e32 v244, 2, v73
	v_add_u32_e32 v208, v89, v244
	v_add_u32_e32 v209, 0x400, v208
	v_add_u32_e32 v244, s55, v82
	v_cndmask_b32_e64 v244, v244, v71, s[44:45]
	v_ashrrev_i32_e32 v245, 31, v244
	v_lshl_add_u64 v[244:245], v[244:245], 0, s[88:89]
	v_lshlrev_b64 v[244:245], 11, v[244:245]
	v_lshl_add_u64 v[210:211], v[48:49], 0, v[244:245]
	v_lshlrev_b32_e32 v172, 6, v73
	v_lshl_add_u32 v172, v72, 2, v172
